# lru_pre unit barrier moved after the conv-window load issue
# speedup vs baseline: 1.1540x; 1.0121x over previous
.LBB0_343:
	s_and_b32 s24, s29, 7
	s_lshl_b32 s30, s24, 6
	v_or_b32_e32 v4, s30, v56
	v_or_b32_e32 v0, s28, v4
	v_lshlrev_b32_e32 v0, 2, v0
	v_lshl_add_u64 v[2:3], s[12:13], 0, v[0:1]
	s_movk_i32 s4, 0x1000
	global_load_dword v7, v0, s[12:13]
	global_load_dword v6, v0, s[12:13] offset:2048
	v_add_co_u32_e32 v2, vcc, s4, v2
	v_or_b32_e32 v0, s70, v4
	s_nop 0
	v_addc_co_u32_e32 v3, vcc, 0, v3, vcc
	v_lshlrev_b32_e32 v0, 2, v0
	global_load_dword v10, v[2:3], off
	global_load_dword v8, v[2:3], off offset:2048
	global_load_dword v9, v0, s[14:15]
	s_ashr_i32 s4, s29, 3
	s_and_b32 s25, s4, 31
	s_ashr_i32 s5, s4, 31
	s_lshl_b64 s[22:23], s[4:5], 6
	v_lshl_add_u32 v12, s25, 6, v18
	v_lshlrev_b32_e32 v0, 1, v4
	v_lshl_add_u64 v[2:3], s[22:23], 0, v[18:19]
	v_lshl_add_u64 v[4:5], s[18:19], 0, v[0:1]
	v_mad_u64_u32 v[14:15], s[26:27], v2, s79, v[4:5]
	v_mad_i32_i24 v15, v3, s79, v15
	s_mov_b32 s98, 0x2600
	s_mov_b32 s99, 0
	global_load_ushort v84, v[14:15], off
	v_lshl_add_u64 v[14:15], v[14:15], 0, s[98:99]
	global_load_ushort v85, v[14:15], off
	v_lshl_add_u64 v[14:15], v[14:15], 0, s[98:99]
	global_load_ushort v86, v[14:15], off
	v_lshl_add_u64 v[14:15], v[14:15], 0, s[98:99]
	global_load_ushort v87, v[14:15], off
	v_lshl_add_u64 v[14:15], v[14:15], 0, s[98:99]
	global_load_ushort v88, v[14:15], off
	v_lshl_add_u64 v[14:15], v[14:15], 0, s[98:99]
	global_load_ushort v89, v[14:15], off
	v_lshl_add_u64 v[14:15], v[14:15], 0, s[98:99]
	global_load_ushort v90, v[14:15], off
	v_lshl_add_u64 v[14:15], v[14:15], 0, s[98:99]
	global_load_ushort v91, v[14:15], off
	v_lshl_add_u64 v[14:15], v[14:15], 0, s[98:99]
	global_load_ushort v92, v[14:15], off
	v_lshl_add_u64 v[14:15], v[14:15], 0, s[98:99]
	global_load_ushort v93, v[14:15], off
	v_lshl_add_u64 v[14:15], v[14:15], 0, s[98:99]
	global_load_ushort v94, v[14:15], off
	v_cmp_lt_i32_e32 vcc, 0, v12
	s_waitcnt vmcnt(0)
	s_barrier
	v_lshlrev_b32_e32 v11, 16, v84
	v_lshlrev_b32_e32 v0, 16, v85
	v_lshlrev_b32_e32 v14, 16, v86
	v_lshlrev_b32_e32 v13, 16, v87
	v_lshlrev_b32_e32 v16, 16, v88
	v_lshlrev_b32_e32 v15, 16, v89
	v_lshlrev_b32_e32 v33, 16, v90
	v_lshlrev_b32_e32 v17, 16, v91
	v_lshlrev_b32_e32 v36, 16, v92
	v_lshlrev_b32_e32 v35, 16, v93
	v_lshlrev_b32_e32 v12, 16, v94
	v_cndmask_b32_e32 v11, 0, v11, vcc
	v_cndmask_b32_e32 v0, 0, v0, vcc
	v_cndmask_b32_e32 v14, 0, v14, vcc
	v_fma_f32 v2, v7, v11, v9
	v_fmac_f32_e32 v2, v6, v0
	v_fmac_f32_e32 v2, v10, v14
	v_fma_f32 v0, v7, v0, v9
	v_fmac_f32_e32 v2, v8, v13
	v_add_u32_e32 v3, v57, v59
	v_fmac_f32_e32 v0, v6, v14
	ds_write_b32 v3, v2
	v_bfe_u32 v3, v2, 16, 1
	v_fmac_f32_e32 v0, v10, v13
	v_add3_u32 v2, v2, v3, s78
	v_fmac_f32_e32 v0, v8, v16
	ds_write_b16_d16_hi v62, v2 offset:16384
	v_bfe_u32 v2, v0, 16, 1
	ds_write_b32 v63, v0
	v_add3_u32 v0, v0, v2, s78
	ds_write_b16_d16_hi v62, v0 offset:16528
	v_fma_f32 v0, v7, v14, v9
	v_fmac_f32_e32 v0, v6, v13
	v_fmac_f32_e32 v0, v10, v16
	v_fmac_f32_e32 v0, v8, v15
	v_bfe_u32 v2, v0, 16, 1
	ds_write_b32 v64, v0
	v_add3_u32 v0, v0, v2, s78
	ds_write_b16_d16_hi v62, v0 offset:16672
	v_fma_f32 v0, v7, v13, v9
	v_fmac_f32_e32 v0, v6, v16
	v_fmac_f32_e32 v0, v10, v15
	v_fmac_f32_e32 v0, v8, v33
	v_bfe_u32 v2, v0, 16, 1
	ds_write_b32 v65, v0
	v_add3_u32 v0, v0, v2, s78
	ds_write_b16_d16_hi v62, v0 offset:16816
	v_fma_f32 v0, v7, v16, v9
	v_fmac_f32_e32 v0, v6, v15
	v_fmac_f32_e32 v0, v10, v33
	v_fmac_f32_e32 v0, v8, v17
	v_bfe_u32 v2, v0, 16, 1
	ds_write_b32 v66, v0
	v_add3_u32 v0, v0, v2, s78
	ds_write_b16_d16_hi v62, v0 offset:16960
	v_fma_f32 v0, v7, v15, v9
	v_fmac_f32_e32 v0, v6, v33
	v_fmac_f32_e32 v0, v10, v17
	v_fmac_f32_e32 v0, v8, v36
	v_bfe_u32 v2, v0, 16, 1
	ds_write_b32 v67, v0
	v_add3_u32 v0, v0, v2, s78
	ds_write_b16_d16_hi v62, v0 offset:17104
	v_fma_f32 v0, v7, v33, v9
	v_fmac_f32_e32 v0, v6, v17
	v_fmac_f32_e32 v0, v10, v36
	v_fmac_f32_e32 v9, v7, v17
	v_fmac_f32_e32 v0, v8, v35
	v_fmac_f32_e32 v9, v6, v36
	v_bfe_u32 v2, v0, 16, 1
	v_fmac_f32_e32 v9, v10, v35
	ds_write_b32 v68, v0
	v_add3_u32 v0, v0, v2, s78
	v_fmac_f32_e32 v9, v8, v12
	s_lshl_b32 s72, s24, 13
	ds_write_b16_d16_hi v62, v0 offset:17248
	v_bfe_u32 v0, v9, 16, 1
	v_lshl_add_u64 v[36:37], v[20:21], 0, s[72:73]
	v_mov_b32_e32 v33, v1
	v_add3_u32 v0, v9, v0, s78
	v_lshl_add_u64 v[40:41], v[36:37], 0, v[32:33]
	ds_write_b32 v69, v9
	ds_write_b16_d16_hi v70, v0 offset:16384
	s_waitcnt lgkmcnt(0)
	s_barrier
	global_load_dwordx4 v[6:9], v[40:41], off
	ds_read_b128 v[2:5], v58 offset:16384
	v_lshl_add_u64 v[38:39], v[22:23], 0, s[72:73]
	v_lshl_add_u64 v[44:45], v[38:39], 0, v[32:33]
	s_cmp_lg_u32 s25, 0
	s_cselect_b64 s[24:25], -1, 0
	v_mov_b32_e32 v75, 1.0
	s_or_b64 s[24:25], s[24:25], s[20:21]
	s_waitcnt vmcnt(0) lgkmcnt(0)
	v_mfma_f32_16x16x32_bf16 v[10:13], v[2:5], v[6:9], 0
	global_load_dwordx4 v[6:9], v[44:45], off
	s_nop 0
	global_load_dwordx4 v[40:43], v[40:41], off offset:64
	s_waitcnt vmcnt(1)
	v_mfma_f32_16x16x32_bf16 v[14:17], v[2:5], v[6:9], 0
	ds_read_b128 v[6:9], v58 offset:16448
	s_waitcnt vmcnt(0) lgkmcnt(0)
	v_mfma_f32_16x16x32_bf16 v[10:13], v[6:9], v[40:43], v[10:13]
	global_load_dwordx4 v[40:43], v[44:45], off offset:64
	s_waitcnt vmcnt(0)
	v_mfma_f32_16x16x32_bf16 v[14:17], v[6:9], v[40:43], v[14:17]
	v_add_u32_e32 v40, s30, v60
	v_add_u32_e32 v0, s70, v40
	v_lshlrev_b64 v[42:43], 2, v[0:1]
	v_lshl_add_u64 v[44:45], s[16:17], 0, v[42:43]
	global_load_dword v35, v[44:45], off
	v_lshl_add_u64 v[44:45], s[8:9], 0, v[42:43]
	v_lshl_add_u64 v[42:43], s[10:11], 0, v[42:43]
	global_load_dword v0, v[42:43], off
	global_load_dword v55, v[44:45], off
	v_mov_b32_e32 v42, 0xff800000
	v_mov_b32_e32 v43, 1.0
	s_waitcnt vmcnt(1)
	v_max_f32_e64 v33, -v0, -v0
	v_mul_f32_e64 v0, |v0|, s82
	v_exp_f32_e32 v0, v0
	v_max_f32_e32 v33, 0, v33
	v_add_f32_e32 v0, 1.0, v0
	v_cmp_gt_f32_e32 vcc, s74, v0
	s_nop 1
	v_cndmask_b32_e64 v41, 0, 32, vcc
	v_ldexp_f32 v0, v0, v41
	v_log_f32_e32 v0, v0
	s_nop 0
	v_mul_f32_e32 v41, 0x3f317217, v0
	v_fma_f32 v41, v0, s83, -v41
	v_fmac_f32_e32 v41, 0x3377d1cf, v0
	v_fmac_f32_e32 v41, 0x3f317217, v0
	v_cmp_lt_f32_e64 s[4:5], |v0|, s92
	s_nop 1
	v_cndmask_b32_e64 v0, v0, v41, s[4:5]
	v_cndmask_b32_e32 v41, 0, v176, vcc
	v_sub_f32_e32 v0, v0, v41
	v_add_f32_e32 v54, v33, v0
	v_mov_b32_e32 v33, 0xff800000
	s_and_saveexec_b64 s[26:27], s[24:25]
	s_cbranch_execz .LBB0_367
	v_add_f32_e32 v0, v10, v35
	v_mul_f32_e32 v0, 0xbfb8aa3b, v0
	v_exp_f32_e32 v0, v0
	s_nop 0
	v_add_f32_e32 v0, 1.0, v0
	v_rcp_f32_e32 v0, v0
	s_nop 0
	v_mul_f32_e32 v0, 0xc1000000, v0
	v_mul_f32_e32 v42, v0, v54
	v_add_f32_e32 v0, v42, v42
	v_mul_f32_e32 v10, 0x3fb8aa3b, v0
	v_rndne_f32_e32 v10, v10
	v_fmamk_f32 v41, v10, 0xbf317218, v0
	v_fmac_f32_e32 v41, 0x3102e308, v10
	v_fmamk_f32 v43, v41, 0x395133b1, v171
	v_cmp_eq_f32_e32 vcc, s2, v10
	v_cvt_i32_f32_e32 v10, v10
	v_fmaak_f32 v43, v41, v43, 0x3c0887f9
	v_fmaak_f32 v43, v41, v43, 0x3d2aaa81
	v_fmaak_f32 v43, v41, v43, 0x3e2aaaab
	v_fma_f32 v43, v41, v43, 0.5
	v_ldexp_f32 v10, 1.0, v10
	v_mul_f32_e32 v43, v41, v43
	v_cndmask_b32_e32 v10, v10, v178, vcc
	v_fmac_f32_e32 v41, v41, v43
	v_add_f32_e32 v43, -1.0, v10
	v_fmac_f32_e32 v43, v10, v41
	v_add_f32_e32 v10, v43, v43
	v_cndmask_b32_e32 v10, v43, v10, vcc
	v_max_f32_e64 v10, -v10, 0
	v_cmp_gt_f32_e32 vcc, s93, v10
	v_mul_f32_e32 v41, 0x4f800000, v10
	s_nop 0
	v_cndmask_b32_e32 v10, v10, v41, vcc
	v_sqrt_f32_e32 v41, v10
	s_nop 0
	v_add_u32_e32 v43, -1, v41
	v_fma_f32 v44, -v43, v41, v10
	v_cmp_ge_f32_e64 s[4:5], 0, v44
	v_add_u32_e32 v44, 1, v41
	s_nop 0
	v_cndmask_b32_e64 v43, v41, v43, s[4:5]
	v_fma_f32 v41, -v44, v41, v10
	v_cmp_lt_f32_e64 s[4:5], 0, v41
	s_nop 1
	v_cndmask_b32_e64 v41, v43, v44, s[4:5]
	v_mul_f32_e32 v43, 0x37800000, v41
	v_cndmask_b32_e32 v41, v41, v43, vcc
	v_cmp_class_f32_e32 vcc, v10, v170
	s_nop 1
	v_cndmask_b32_e32 v10, v41, v10, vcc
	v_cmp_nlt_f32_e32 vcc, s3, v0
	s_nop 1
	v_cndmask_b32_e32 v10, 0, v10, vcc
	v_cmp_ngt_f32_e32 vcc, s52, v0
	s_nop 1
	v_cndmask_b32_e32 v43, 1.0, v10, vcc
